# adds PLE-gate layer0 third round moved after the grid barrier (overlaps layer1 in-proj), flag wait before sample-row in-proj units
# speedup vs baseline: 1.0048x; 1.0048x over previous
; #define GRID_BAR(k) grid_bar(bar, (unsigned)((k) + 1), (unsigned)G, (unsigned)bid, wave == 0 && lane_id() == 0)
; __device__ __forceinline__ void grid_bar(unsigned* bar, unsigned k, unsigned G, unsigned bid, bool leader) {
;     ...
;     __syncthreads();
; template <int l>
; __device__ __forceinline__ void run_layer(LAS unsigned char* lds, unsigned char* ws_in, float* out_in, const float* x_p, const float* x_s, const PIn* pin, const int G, const int bid, const int wave) {
;     ...
;         GRID_BAR(6 * l + 5);
;         {
;             pg8::RowOrder<DM / 256> S; S.init(G, bid);
;             EpiPG E{ws, out, (2 + 2 * l) * MT};
;             pg8::gemm_phase<DM, EpiPG, pg8::RowOrder<DM / 256>>(lds, HB, (const bf16*)(wb + W_PG), S, E, wave);
.LBB0_809:
	s_or_b64 exec, exec, s[6:7]
	s_mov_b32 s78, 0
	s_mov_b32 s76, s9
	s_mov_b32 s77, s5
	s_barrier

;     __device__ __forceinline__ bool next(int i, Unit& u) const {
;         constexpr int NU = (33792 / BM) * NN;
;         const int L = i * G + ((NU - i * G < G) ? vp : v); if (L >= NU) return false;
;         constexpr int NM = 33792 / BM, NFULL = (NM / 8) * 8 * NN;
;         if (L < NFULL) { const int g = L / (8 * NN), idx = L % (8 * NN); u.pm = g * 8 + (idx & 7); u.pn = idx >> 3; }
;         else { constexpr int GS = NM % 8 ? NM % 8 : 8; const int idx = L - NFULL; u.pm = (NM / 8) * 8 + idx % GS; u.pn = idx / GS; }
; template <int KK, class Epi, class Sched, bool ALIGN_EPI = true>
; __device__ __forceinline__ void gemm_phase(LAS unsigned char* lds, const bf16* gA, const bf16* gBt, const Sched& S, const Epi& E, const int wid) {
;     ...
;     if (!S.next(0, cur)) return;
.LBB0_811:
	v_readlane_b32 s2, v249, 17
	v_readlane_b32 s3, v249, 18
	s_and_b64 s[2:3], s[2:3], exec
	s_cselect_b32 s2, s1, s0
	s_cmp_eq_u32 s78, 1
	s_cbranch_scc0 .Lp6a_f0
	s_add_i32 s2, s86, 0x110
.Lp6a_f0:
	s_cmpk_lt_i32 s2, 0x210
	v_mov_b32_e32 v0, v196
	s_cselect_b64 s[6:7], -1, 0
	s_cmpk_gt_i32 s2, 0x20f
	s_cbranch_scc1 .LBB0_818
	s_cmpk_gt_i32 s2, 0x1ff
	s_cbranch_scc0 .LBB0_816
	s_add_i32 s3, s2, 0xfffffe00
	s_and_b32 s10, s2, 3
	s_or_b32 s52, s10, 0x80
	s_lshr_b32 s50, s3, 2
	s_cbranch_execz .LBB0_817
	s_branch .LBB0_818

;     __device__ __forceinline__ bool next(int i, Unit& u) const {
;         constexpr int NU = (33792 / BM) * NN;
;         const int L = i * G + ((NU - i * G < G) ? vp : v); if (L >= NU) return false;
;         constexpr int NM = 33792 / BM, NFULL = (NM / 8) * 8 * NN;
;         if (L < NFULL) { const int g = L / (8 * NN), idx = L % (8 * NN); u.pm = g * 8 + (idx & 7); u.pn = idx >> 3; }
;         else { constexpr int GS = NM % 8 ? NM % 8 : 8; const int idx = L - NFULL; u.pm = (NM / 8) * 8 + idx % GS; u.pn = idx / GS; }
; template <int KK, class Epi, class Sched, bool ALIGN_EPI = true>
; __device__ __forceinline__ void gemm_phase(LAS unsigned char* lds, const bf16* gA, const bf16* gBt, const Sched& S, const Epi& E, const int wid) {
;     ...
;         const bool has_next = S.next(ui + 1, nxt);
.LBB0_824:
	s_add_i32 s61, s61, 1
	s_mul_i32 s15, s61, s64
	s_sub_i32 s17, 0x210, s15
	s_cmp_lt_i32 s17, s64
	s_cselect_b32 s17, s1, s0
	s_add_i32 s15, s17, s15
	s_cmp_lg_u32 s64, 0x100
	s_cbranch_scc1 .Lp6a_s
	s_cmp_eq_u32 s78, 1
	s_cbranch_scc1 .Lp6a_none
	s_cmpk_lt_i32 s15, 0x200
	s_cbranch_scc1 .Lp6a_s

;     __device__ __forceinline__ bool next(int i, Unit& u) const {
;     ...
;         const int L = i * G + ((NU - i * G < G) ? vp : v); if (L >= NU) return false;
;         constexpr int NM = 33792 / BM, NFULL = (NM / 8) * 8 * NN;
;         if (L < NFULL) { const int g = L / (8 * NN), idx = L % (8 * NN); u.pm = g * 8 + (idx & 7); u.pn = idx >> 3; }
;         else { constexpr int GS = NM % 8 ? NM % 8 : 8; const int idx = L - NFULL; u.pm = (NM / 8) * 8 + idx % GS; u.pn = idx / GS; }
.Lp6a_s:
	s_cmpk_lt_i32 s15, 0x210
	s_cselect_b64 s[30:31], -1, 0
	s_cmpk_gt_i32 s15, 0x20f
	s_cbranch_scc1 .LBB0_829
	s_cmpk_gt_i32 s15, 0x1ff
	s_mov_b64 s[36:37], -1
	s_cbranch_scc0 .LBB0_827
	s_add_i32 s16, s15, 0xfffffe00
	s_and_b32 s14, s15, 3
	s_bitset1_b32 s14, 7
	s_lshr_b32 s16, s16, 2
	s_mov_b64 s[36:37], 0

; __device__ __forceinline__ unsigned cvt_pk(float lo, float hi) { unsigned r; asm("v_cvt_pk_bf16_f32 %0, %1, %2" : "=v"(r) : "v"(lo), "v"(hi)); return r; }
; __device__ __forceinline__ int lane_id() { int l = __builtin_amdgcn_mbcnt_hi(~0u, __builtin_amdgcn_mbcnt_lo(~0u, 0u)); asm volatile("" : "+v"(l)); return l; }
;     ...
;     constexpr size_t NA = (size_t)16 * 512 * 512, NB = (size_t)16 * 128 * 128;
;     for (size_t i = gtid * 8; i < NA; i += gth * 8) {
;         const size_t gi = (size_t)l * NA + i;
;         const f32x4 a = *(const f32x4*)(I.cak + gi), b = *(const f32x4*)(I.cak + gi + 4), c = *(const f32x4*)(I.cav + gi), d = *(const f32x4*)(I.cav + gi + 4);
;         v4u w; w.x = cvt_pk(a[0], a[1]); w.y = cvt_pk(a[2], a[3]); w.z = cvt_pk(b[0], b[1]); w.w = cvt_pk(b[2], b[3]);
;         *(v4u*)((bf16*)(ws + WS_CKA) + gi) = w;
;         w.x = cvt_pk(c[0], c[1]); w.y = cvt_pk(c[2], c[3]); w.z = cvt_pk(d[0], d[1]); w.w = cvt_pk(d[2], d[3]);
;         *(v4u*)((bf16*)(ws + WS_CVA) + gi) = w;
;         if (((i >> 9) & 511) >= 64) { float* dk = out + O_AKS + gi - 32768; float* dv = out + O_AVS + gi - 32768;
;             *(f32x4*)dk = a; *(f32x4*)(dk + 4) = b; *(f32x4*)dv = c; *(f32x4*)(dv + 4) = d; }
; template <int l>
; __device__ __forceinline__ void run_layer(LAS unsigned char* lds, unsigned char* ws_in, float* out_in, const float* x_p, const float* x_s, const PIn* pin, const int G, const int bid, const int wave) {
;     ...
;             if (l == 0) {
;                 const int nbusy = (MT / 256 * 4) % G;
;                 if (S.vp >= nbusy) { const int lane = lane_id(); const PIn I = *pin;
;                     conv_p_caches(ws, out, I, 1, (size_t)(S.vp - nbusy) * (NWAVES * 64) + wave * 64 + lane, (size_t)(G - nbusy) * (NWAVES * 64), 2); }
.LBB0_853:
	s_cmp_eq_u32 s78, 1
	s_cbranch_scc1 .Lp6a_done2
	s_cmp_lt_i32 s1, s8
	s_cbranch_scc1 .LBB0_865
	s_sub_i32 s0, s1, s8
	s_mov_b32 s1, 0
	s_lshl_b64 s[0:1], s[0:1], 9
	v_readlane_b32 s2, v249, 59
	v_mov_b32_e32 v0, v196
	v_readlane_b32 s3, v249, 60
	s_add_u32 s0, s0, s2
	s_addc_u32 s1, s1, s3
	s_waitcnt lgkmcnt(0)
	v_ashrrev_i32_e32 v1, 31, v0
	v_lshl_add_u64 v[0:1], s[0:1], 0, v[0:1]
	s_sub_i32 s0, s64, s8
	s_ashr_i32 s1, s0, 31
	s_lshl_b64 s[6:7], s[0:1], 12
	v_lshlrev_b64 v[16:17], 3, v[0:1]
	s_mov_b64 s[0:1], 0x400000
	v_cmp_gt_u64_e32 vcc, s[0:1], v[16:17]
	v_lshlrev_b64 v[18:19], 5, v[0:1]
	v_lshl_add_u64 v[20:21], v[0:1], 4, s[44:45]
	s_and_saveexec_b64 s[10:11], vcc
	s_cbranch_execz .LBB0_859
	s_ashr_i32 s9, s8, 31
	s_lshl_b64 s[0:1], s[64:65], 14
	s_lshl_b64 s[2:3], s[8:9], 14
	s_sub_u32 s0, s0, s2
	s_subb_u32 s1, s1, s3
	s_mov_b64 s[2:3], 0x1c980000
	v_lshl_add_u64 v[22:23], v[20:21], 0, s[2:3]
	s_lshl_b64 s[2:3], s[64:65], 13
	s_lshl_b64 s[12:13], s[8:9], 13
	s_sub_u32 s12, s2, s12
	s_subb_u32 s13, s3, s13
	s_mov_b64 s[14:15], 0
	s_mov_b64 s[16:17], 0x1000000
	s_mov_b32 s2, 0x1000000
	s_mov_b32 s3, 0xff000000
	v_mov_b32_e32 v25, 0
	s_mov_b64 s[30:31], 0x3fffff
	s_mov_b64 s[36:37], s[46:47]
	v_mov_b64_e32 v[26:27], v[16:17]
	s_branch .LBB0_857

; #define GRID_BAR(k) grid_bar(bar, (unsigned)((k) + 1), (unsigned)G, (unsigned)bid, wave == 0 && lane_id() == 0)
; __device__ __forceinline__ void grid_bar(unsigned* bar, unsigned k, unsigned G, unsigned bid, bool leader) {
;     asm volatile("s_waitcnt vmcnt(0) lgkmcnt(0)" ::: "memory");
;     __syncthreads();
;     if (leader) {
;         const unsigned g = bid & 7u, gsz = (G - g + 7u) >> 3, ng = G < 8u ? G : 8u;
;         unsigned* gcnt = bar + 16 * (1 + g); unsigned* ggen = bar + 16 * (9 + g); unsigned* top = bar + 16 * 17;
;         __builtin_amdgcn_fence(__ATOMIC_RELEASE, "agent");
;         asm volatile("s_waitcnt vmcnt(0)" ::: "memory");
;         const unsigned old = __hip_atomic_fetch_add(gcnt, 1u, __ATOMIC_RELAXED, __HIP_MEMORY_SCOPE_AGENT);
;         if (old + 1u == k * gsz) {
;             __hip_atomic_fetch_add(top, 1u, __ATOMIC_RELAXED, __HIP_MEMORY_SCOPE_AGENT);
;             while (__hip_atomic_load(top, __ATOMIC_RELAXED, __HIP_MEMORY_SCOPE_AGENT) < k * ng) __builtin_amdgcn_s_sleep(1);
;             __hip_atomic_fetch_add(ggen, 1u, __ATOMIC_RELAXED, __HIP_MEMORY_SCOPE_AGENT);
;         } else {
;             while (__hip_atomic_load(ggen, __ATOMIC_RELAXED, __HIP_MEMORY_SCOPE_AGENT) < k) __builtin_amdgcn_s_sleep(1);
;         }
;         __builtin_amdgcn_fence(__ATOMIC_ACQUIRE, "agent");
;         asm volatile("s_waitcnt vmcnt(0)" ::: "memory");
;     }
;     __syncthreads();
; template <int l>
; __device__ __forceinline__ void run_layer(LAS unsigned char* lds, unsigned char* ws_in, float* out_in, const float* x_p, const float* x_s, const PIn* pin, const int G, const int bid, const int wave) {
;     ...
;         GRID_BAR(6 * l + 6);
.LBB0_882:
	s_or_b64 exec, exec, s[6:7]
	s_barrier
	s_cmp_lg_u32 s64, 0x100
	s_cbranch_scc1 .Lp6a_after
	s_cmp_lg_u32 s78, 0
	s_cbranch_scc1 .Lp6a_after
	s_cmp_lt_u32 s86, 0xf0
	s_cbranch_scc1 .Lp6a_after
	s_mov_b32 s9, s76
	s_mov_b32 s5, s77
	s_mov_b32 s78, 1
	s_branch .Lp6a_entry
.Lp6a_done2:
	v_readlane_b32 s80, v249, 1
	v_readlane_b32 s81, v249, 2
	s_waitcnt vmcnt(0) lgkmcnt(0)
	v_readlane_b32 s79, v249, 0
	s_nop 3
	s_cmp_lg_u32 s79, 0
	s_cbranch_scc1 .Lp6a_rel_done
	buffer_wbl2 sc1
	s_waitcnt vmcnt(0)
	v_mov_b32_e32 v4, 0
	v_mov_b32_e32 v5, 1
	s_mov_b64 s[82:83], exec
	s_mov_b64 exec, 1
	global_atomic_add v4, v5, s[80:81] offset:3464
	s_waitcnt vmcnt(0)
	s_mov_b64 exec, s[82:83]
.Lp6a_rel_done:
	s_mov_b32 s78, 2
.Lp6a_after:
	v_readlane_b32 s0, v249, 3
	v_readlane_b32 s2, v249, 5
	v_readlane_b32 s3, v249, 6
	s_mov_b64 s[22:23], s[2:3]
	s_and_b64 vcc, exec, s[74:75]
	s_mov_b32 s5, s86
	v_readlane_b32 s1, v249, 4
	s_cbranch_vccz .LBB0_887
	s_and_b64 vcc, exec, s[74:75]
	s_mov_b32 s29, s5
	s_cbranch_vccz .LBB0_888

;     __device__ __forceinline__ bool next(int i, Unit& u) const {
;         constexpr int NU = (33792 / BM) * NN;
;         const int L = i * G + ((NU - i * G < G) ? vp : v); if (L >= NU) return false;
;         constexpr int NM = 33792 / BM, NFULL = (NM / 8) * 8 * NN;
;         if (L < NFULL) { const int g = L / (8 * NN), idx = L % (8 * NN); u.pm = g * 8 + (idx & 7); u.pn = idx >> 3; }
;         else { constexpr int GS = NM % 8 ? NM % 8 : 8; const int idx = L - NFULL; u.pm = (NM / 8) * 8 + idx % GS; u.pn = idx / GS; }
;         return true;
;     }
; template <int KK, class Epi, class Sched, bool ALIGN_EPI = true>
; __device__ __forceinline__ void gemm_phase(LAS unsigned char* lds, const bf16* gA, const bf16* gBt, const Sched& S, const Epi& E, const int wid) {
;     ...
;         const bool has_next = S.next(ui + 1, nxt);
.LBB0_897:
	s_add_i32 s1, s1, 1
	s_mul_i32 s2, s1, s64
	s_sub_i32 s3, 0x4a4, s2
	s_cmp_lt_i32 s3, s64
	s_cselect_b32 s3, s29, s5
	s_add_i32 s2, s3, s2
	s_cmpk_lt_i32 s2, 0x4a4
	s_cselect_b64 s[52:53], -1, 0
	s_cmpk_gt_i32 s2, 0x4a3
	s_cbranch_scc1 .LBB0_902
	s_cmpk_gt_i32 s2, 0x47f
	s_mov_b64 s[10:11], -1
	s_cbranch_scc0 .LBB0_900
	s_cmp_lg_u32 s64, 0x100
	s_cbranch_scc1 .Lp6ac_ok
	v_mov_b32_e32 v0, 0
.Lp6ac_poll:
	global_load_dword v1, v0, s[20:21] offset:3464 sc1
	s_waitcnt vmcnt(0)
	v_readfirstlane_b32 s3, v1
	s_nop 0
	s_cmp_ge_u32 s3, 16
	s_cbranch_scc1 .Lp6ac_ok
	s_sleep 2
	s_branch .Lp6ac_poll
.Lp6ac_ok:
	buffer_inv sc1
	s_waitcnt vmcnt(0)
	s_add_i32 s3, s2, 0xfffffb80
	s_and_b32 s10, s2, 3
	s_or_b32 s48, s10, 0x80
	s_lshr_b32 s50, s3, 2
	s_mov_b64 s[10:11], 0
